# grid-barrier spin loops poll with s_sleep 4 instead of s_sleep 1 (less polling traffic; 8x barrier probe optimum)
# speedup vs baseline: 1.0084x; 1.0084x over previous
; __device__ __forceinline__ unsigned xb_ld(unsigned* p)              { return __hip_atomic_load(p, __ATOMIC_RELAXED, __HIP_MEMORY_SCOPE_AGENT); }
; __device__ __forceinline__ void xcd_barrier_complete(unsigned* bar, unsigned x, unsigned& nloc, unsigned& nx) {
;     const unsigned G = gridDim.x * gridDim.y * gridDim.z;
;     unsigned sum, cnt, mine, sp = 0u;
;     for (;;) {
;         sum = 0u; cnt = 0u; mine = 0u;
; #pragma unroll
;         for (unsigned j = 0; j < 16; ++j) { const unsigned c = xb_ld(&bar[XB_XCNT(j)]); sum += c; cnt += (c > 0u) ? 1u : 0u; mine = (j == x) ? c : mine; }
;         if (sum == G) break;
;         __builtin_amdgcn_s_sleep(1);
;         if ((++sp & 255u) == 0u) { if (xb_ld(&bar[XB_TMO])) break; if (sp > XB_SPIN_CAP) { atomicAdd(&bar[XB_TMO], 1u); break; } }
;     }
.LBB0_68:
	global_load_dword v17, v1, s[12:13] offset:1024 sc1
	global_load_dword v0, v1, s[12:13] offset:1280 sc1
	s_waitcnt lgkmcnt(0)
	global_load_dword v2, v1, s[12:13] offset:1536 sc1
	global_load_dword v3, v1, s[12:13] offset:1792 sc1
	global_load_dword v4, v1, s[12:13] offset:2048 sc1
	global_load_dword v5, v1, s[12:13] offset:2304 sc1
	global_load_dword v6, v1, s[12:13] offset:2560 sc1
	global_load_dword v7, v1, s[12:13] offset:2816 sc1
	global_load_dword v8, v1, s[12:13] offset:3072 sc1
	global_load_dword v9, v1, s[12:13] offset:3328 sc1
	global_load_dword v10, v1, s[12:13] offset:3584 sc1
	global_load_dword v11, v1, s[12:13] offset:3840 sc1
	global_load_dword v12, v1, s[14:15] sc1
	global_load_dword v13, v1, s[16:17] sc1
	global_load_dword v14, v1, s[18:19] sc1
	global_load_dword v15, v1, s[20:21] sc1
	v_readlane_b32 s4, v254, 27
	s_mov_b64 s[22:23], -1
	s_mov_b64 s[24:25], -1
	s_waitcnt vmcnt(14)
	v_add_u32_e32 v18, v0, v17
	s_waitcnt vmcnt(13)
	v_add_u32_e32 v18, v18, v2
	s_waitcnt vmcnt(12)
	v_add_u32_e32 v18, v18, v3
	s_waitcnt vmcnt(11)
	v_add_u32_e32 v18, v18, v4
	s_waitcnt vmcnt(10)
	v_add_u32_e32 v18, v18, v5
	s_waitcnt vmcnt(9)
	v_add_u32_e32 v18, v18, v6
	s_waitcnt vmcnt(8)
	v_add_u32_e32 v18, v18, v7
	s_waitcnt vmcnt(7)
	v_add_u32_e32 v18, v18, v8
	s_waitcnt vmcnt(6)
	v_add_u32_e32 v18, v18, v9
	s_waitcnt vmcnt(5)
	v_add_u32_e32 v18, v18, v10
	s_waitcnt vmcnt(4)
	v_add_u32_e32 v18, v18, v11
	s_waitcnt vmcnt(3)
	v_add_u32_e32 v18, v18, v12
	s_waitcnt vmcnt(2)
	v_add_u32_e32 v18, v18, v13
	s_waitcnt vmcnt(1)
	v_add_u32_e32 v18, v18, v14
	s_waitcnt vmcnt(0)
	v_add_u32_e32 v18, v18, v15
	v_cmp_eq_u32_e32 vcc, s4, v18
	s_cbranch_vccnz .LBB0_67
	s_and_b32 s4, s3, 0xff
	s_cmp_eq_u32 s4, 0
	s_mov_b64 s[26:27], -1
	s_sleep 4
	s_cbranch_scc0 .LBB0_72
	global_load_dword v18, v1, s[12:13] offset:512 sc1
	s_waitcnt vmcnt(0)
	v_cmp_eq_u32_e32 vcc, 0, v18
	s_cbranch_vccnz .LBB0_74
	s_mov_b64 s[26:27], 0

; __device__ __forceinline__ unsigned xb_ld(unsigned* p)              { return __hip_atomic_load(p, __ATOMIC_RELAXED, __HIP_MEMORY_SCOPE_AGENT); }
; __device__ __forceinline__ unsigned xb_add(unsigned* p, unsigned v) { return __hip_atomic_fetch_add(p, v, __ATOMIC_RELAXED, __HIP_MEMORY_SCOPE_AGENT); }
; #define XB_SPIN(cond, bar) do { unsigned _sp = 0; while (cond) { __builtin_amdgcn_s_sleep(1); \
;     if ((++_sp & 255u) == 0u) { if (xb_ld(&(bar)[XB_TMO])) break; if (_sp > XB_SPIN_CAP) { atomicAdd(&(bar)[XB_TMO], 1u); break; } } } } while (0)
; __device__ __forceinline__ void xcd_barrier(const XcdBarrier& b) {
;     ...
;             const unsigned tg = og / nx;
;             if (og + 1u == (tg + 1u) * nx) xb_add(&bar[XB_TOPGEN], 1u);
;             else XB_SPIN(xb_ld(&bar[XB_TOPGEN]) == tg, bar);
;             __builtin_amdgcn_fence(__ATOMIC_ACQUIRE, "agent");
;             xb_add(&bar[XB_XGEN(b.x)], 1u);
;             asm volatile("s_waitcnt vmcnt(0)" ::: "memory");
;         } else {
;             XB_SPIN(xb_ld(&bar[XB_XGEN(b.x)]) == gen, bar);
.LBB0_86:
	s_and_b32 s3, s2, 0xff
	s_mov_b64 s[26:27], -1
	s_cmp_lg_u32 s3, 0
	s_mov_b64 s[30:31], -1
	s_sleep 4
	s_cbranch_scc1 .LBB0_89
	global_load_dword v2, v1, s[12:13] offset:512 sc1
	s_waitcnt vmcnt(0)
	v_cmp_eq_u32_e32 vcc, 0, v2
	s_cbranch_vccnz .LBB0_91
	s_mov_b64 s[30:31], 0
	s_mov_b64 s[28:29], -1

; __device__ __forceinline__ unsigned xb_ld(unsigned* p)              { return __hip_atomic_load(p, __ATOMIC_RELAXED, __HIP_MEMORY_SCOPE_AGENT); }
; __device__ __forceinline__ unsigned xb_add(unsigned* p, unsigned v) { return __hip_atomic_fetch_add(p, v, __ATOMIC_RELAXED, __HIP_MEMORY_SCOPE_AGENT); }
; #define XB_SPIN(cond, bar) do { unsigned _sp = 0; while (cond) { __builtin_amdgcn_s_sleep(1); \
;     if ((++_sp & 255u) == 0u) { if (xb_ld(&(bar)[XB_TMO])) break; if (_sp > XB_SPIN_CAP) { atomicAdd(&(bar)[XB_TMO], 1u); break; } } } } while (0)
; __device__ __forceinline__ void xcd_barrier(const XcdBarrier& b) {
;     ...
;             const unsigned tg = og / nx;
;             if (og + 1u == (tg + 1u) * nx) xb_add(&bar[XB_TOPGEN], 1u);
;             else XB_SPIN(xb_ld(&bar[XB_TOPGEN]) == tg, bar);
;             __builtin_amdgcn_fence(__ATOMIC_ACQUIRE, "agent");
;             xb_add(&bar[XB_XGEN(b.x)], 1u);
;             asm volatile("s_waitcnt vmcnt(0)" ::: "memory");
;         } else {
;             XB_SPIN(xb_ld(&bar[XB_XGEN(b.x)]) == gen, bar);
.LBB0_103:
	s_and_b32 s3, s2, 0xff
	s_mov_b64 s[26:27], -1
	s_cmp_lg_u32 s3, 0
	s_mov_b64 s[30:31], -1
	s_sleep 4
	s_cbranch_scc1 .LBB0_106
	global_load_dword v2, v1, s[20:21] sc1
	s_waitcnt vmcnt(0)
	v_cmp_eq_u32_e32 vcc, 0, v2
	s_cbranch_vccnz .LBB0_108
	s_mov_b64 s[30:31], 0
	s_mov_b64 s[28:29], -1

; #define GSYNC() do { KP Pb_ = KARGS(); XcdBarrier b_; b_.bar = (unsigned*)(Pb_->ws + WS_CTL); b_.x = xb_xcc_id(); b_.st = (volatile LAS unsigned*)(lds + LDS_BAR_OFF); xcd_barrier(b_); } while (0)
; __global__ void __launch_bounds__(NTHR, 2) hybrid_fwd(Args args) {
;     ...
;         if (layer == 0) grid.sync(); else GSYNC();
.LBB0_126:
	s_sleep 4
	global_load_dword v2, v1, s[12:13] offset:32 sc1
	s_waitcnt vmcnt(0)
	v_and_b32_e32 v2, 0xffff0000, v2
	v_cmp_ne_u32_e32 vcc, v2, v0
	s_or_b64 s[14:15], vcc, s[14:15]
	s_andn2_b64 exec, exec, s[14:15]
	s_cbranch_execnz .LBB0_126

; __device__ __forceinline__ unsigned xb_ld(unsigned* p)              { return __hip_atomic_load(p, __ATOMIC_RELAXED, __HIP_MEMORY_SCOPE_AGENT); }
; __device__ __forceinline__ void xcd_barrier_complete(unsigned* bar, unsigned x, unsigned& nloc, unsigned& nx) {
;     const unsigned G = gridDim.x * gridDim.y * gridDim.z;
;     unsigned sum, cnt, mine, sp = 0u;
;     for (;;) {
;         sum = 0u; cnt = 0u; mine = 0u;
; #pragma unroll
;         for (unsigned j = 0; j < 16; ++j) { const unsigned c = xb_ld(&bar[XB_XCNT(j)]); sum += c; cnt += (c > 0u) ? 1u : 0u; mine = (j == x) ? c : mine; }
;         if (sum == G) break;
;         __builtin_amdgcn_s_sleep(1);
;         if ((++sp & 255u) == 0u) { if (xb_ld(&bar[XB_TMO])) break; if (sp > XB_SPIN_CAP) { atomicAdd(&bar[XB_TMO], 1u); break; } }
;     }
.LBB0_190:
	global_load_dword v17, v1, s[10:11] offset:1024 sc1
	global_load_dword v0, v1, s[10:11] offset:1280 sc1
	s_waitcnt lgkmcnt(0)
	global_load_dword v2, v1, s[10:11] offset:1536 sc1
	global_load_dword v3, v1, s[10:11] offset:1792 sc1
	global_load_dword v4, v1, s[10:11] offset:2048 sc1
	global_load_dword v5, v1, s[10:11] offset:2304 sc1
	global_load_dword v6, v1, s[10:11] offset:2560 sc1
	global_load_dword v7, v1, s[10:11] offset:2816 sc1
	global_load_dword v8, v1, s[10:11] offset:3072 sc1
	global_load_dword v9, v1, s[10:11] offset:3328 sc1
	global_load_dword v10, v1, s[10:11] offset:3584 sc1
	global_load_dword v11, v1, s[10:11] offset:3840 sc1
	global_load_dword v12, v1, s[12:13] sc1
	global_load_dword v13, v1, s[14:15] sc1
	global_load_dword v14, v1, s[16:17] sc1
	global_load_dword v15, v1, s[18:19] sc1
	v_readlane_b32 s4, v254, 27
	s_mov_b64 s[20:21], -1
	s_mov_b64 s[22:23], -1
	s_waitcnt vmcnt(14)
	v_add_u32_e32 v18, v0, v17
	s_waitcnt vmcnt(13)
	v_add_u32_e32 v18, v18, v2
	s_waitcnt vmcnt(12)
	v_add_u32_e32 v18, v18, v3
	s_waitcnt vmcnt(11)
	v_add_u32_e32 v18, v18, v4
	s_waitcnt vmcnt(10)
	v_add_u32_e32 v18, v18, v5
	s_waitcnt vmcnt(9)
	v_add_u32_e32 v18, v18, v6
	s_waitcnt vmcnt(8)
	v_add_u32_e32 v18, v18, v7
	s_waitcnt vmcnt(7)
	v_add_u32_e32 v18, v18, v8
	s_waitcnt vmcnt(6)
	v_add_u32_e32 v18, v18, v9
	s_waitcnt vmcnt(5)
	v_add_u32_e32 v18, v18, v10
	s_waitcnt vmcnt(4)
	v_add_u32_e32 v18, v18, v11
	s_waitcnt vmcnt(3)
	v_add_u32_e32 v18, v18, v12
	s_waitcnt vmcnt(2)
	v_add_u32_e32 v18, v18, v13
	s_waitcnt vmcnt(1)
	v_add_u32_e32 v18, v18, v14
	s_waitcnt vmcnt(0)
	v_add_u32_e32 v18, v18, v15
	v_cmp_eq_u32_e32 vcc, s4, v18
	s_cbranch_vccnz .LBB0_189
	s_and_b32 s4, s3, 0xff
	s_cmp_eq_u32 s4, 0
	s_mov_b64 s[24:25], -1
	s_sleep 4
	s_cbranch_scc0 .LBB0_194
	global_load_dword v18, v1, s[10:11] offset:512 sc1
	s_waitcnt vmcnt(0)
	v_cmp_eq_u32_e32 vcc, 0, v18
	s_cbranch_vccnz .LBB0_196
	s_mov_b64 s[24:25], 0

; __device__ __forceinline__ unsigned xb_ld(unsigned* p)              { return __hip_atomic_load(p, __ATOMIC_RELAXED, __HIP_MEMORY_SCOPE_AGENT); }
; __device__ __forceinline__ unsigned xb_add(unsigned* p, unsigned v) { return __hip_atomic_fetch_add(p, v, __ATOMIC_RELAXED, __HIP_MEMORY_SCOPE_AGENT); }
; #define XB_SPIN(cond, bar) do { unsigned _sp = 0; while (cond) { __builtin_amdgcn_s_sleep(1); \
;     if ((++_sp & 255u) == 0u) { if (xb_ld(&(bar)[XB_TMO])) break; if (_sp > XB_SPIN_CAP) { atomicAdd(&(bar)[XB_TMO], 1u); break; } } } } while (0)
; __device__ __forceinline__ void xcd_barrier(const XcdBarrier& b) {
;     ...
;             const unsigned tg = og / nx;
;             if (og + 1u == (tg + 1u) * nx) xb_add(&bar[XB_TOPGEN], 1u);
;             else XB_SPIN(xb_ld(&bar[XB_TOPGEN]) == tg, bar);
;             __builtin_amdgcn_fence(__ATOMIC_ACQUIRE, "agent");
;             xb_add(&bar[XB_XGEN(b.x)], 1u);
;             asm volatile("s_waitcnt vmcnt(0)" ::: "memory");
;         } else {
;             XB_SPIN(xb_ld(&bar[XB_XGEN(b.x)]) == gen, bar);
.LBB0_208:
	s_and_b32 s3, s2, 0xff
	s_mov_b64 s[24:25], -1
	s_cmp_lg_u32 s3, 0
	s_mov_b64 s[28:29], -1
	s_sleep 4
	s_cbranch_scc1 .LBB0_211
	global_load_dword v2, v1, s[10:11] offset:512 sc1
	s_waitcnt vmcnt(0)
	v_cmp_eq_u32_e32 vcc, 0, v2
	s_cbranch_vccnz .LBB0_213
	s_mov_b64 s[28:29], 0
	s_mov_b64 s[26:27], -1

; __device__ __forceinline__ unsigned xb_ld(unsigned* p)              { return __hip_atomic_load(p, __ATOMIC_RELAXED, __HIP_MEMORY_SCOPE_AGENT); }
; __device__ __forceinline__ unsigned xb_add(unsigned* p, unsigned v) { return __hip_atomic_fetch_add(p, v, __ATOMIC_RELAXED, __HIP_MEMORY_SCOPE_AGENT); }
; #define XB_SPIN(cond, bar) do { unsigned _sp = 0; while (cond) { __builtin_amdgcn_s_sleep(1); \
;     if ((++_sp & 255u) == 0u) { if (xb_ld(&(bar)[XB_TMO])) break; if (_sp > XB_SPIN_CAP) { atomicAdd(&(bar)[XB_TMO], 1u); break; } } } } while (0)
; __device__ __forceinline__ void xcd_barrier(const XcdBarrier& b) {
;     ...
;             const unsigned tg = og / nx;
;             if (og + 1u == (tg + 1u) * nx) xb_add(&bar[XB_TOPGEN], 1u);
;             else XB_SPIN(xb_ld(&bar[XB_TOPGEN]) == tg, bar);
;             __builtin_amdgcn_fence(__ATOMIC_ACQUIRE, "agent");
;             xb_add(&bar[XB_XGEN(b.x)], 1u);
;             asm volatile("s_waitcnt vmcnt(0)" ::: "memory");
;         } else {
;             XB_SPIN(xb_ld(&bar[XB_XGEN(b.x)]) == gen, bar);
.LBB0_225:
	s_and_b32 s3, s2, 0xff
	s_mov_b64 s[24:25], -1
	s_cmp_lg_u32 s3, 0
	s_mov_b64 s[28:29], -1
	s_sleep 4
	s_cbranch_scc1 .LBB0_228
	global_load_dword v2, v1, s[18:19] sc1
	s_waitcnt vmcnt(0)
	v_cmp_eq_u32_e32 vcc, 0, v2
	s_cbranch_vccnz .LBB0_230
	s_mov_b64 s[28:29], 0
	s_mov_b64 s[26:27], -1
